# GEMM unit bookkeeping: epilogue prefetch reuses the already decoded (pm,pn) of the next unit; unit decode's divide by the constant group width 4 is a shift and a mask
# baseline (speedup 1.0000x reference)
;     __host__ __device__ bool next(int i, Unit& u) const {
;         const long L = (long)i * G + c; if (L >= nwg) return false;
;         int wgid = (int)L; { const int q = nwg / NXCD, r = nwg % NXCD, xcd = wgid % NXCD, off = wgid / NXCD; wgid = (xcd < r ? xcd * (q + 1) : r * (q + 1) + (xcd - r) * q) + off; }
;         const int nig = WGM * nN, gid = wgid / nig, fm = gid * WGM, gsz = (nM - fm) < WGM ? (nM - fm) : WGM;
;         u.pm = fm + ((wgid % nig) % gsz); u.pn = (wgid % nig) / gsz; return true;
; template <class Epi, class Sched, bool ALIGN_EPI = false, bool SP2 = false>
; __device__ __forceinline__ void gemm_phase(PG8_LAS unsigned char* lds, const Gemm g, const Sched& S, const Epi& E, const int tid) {
;     ...
;         const bool has_next = S.next(ui + 1, nxt);
.LBB0_59:
	s_add_i32 s9, s27, 1
	s_mul_i32 s0, s9, s86
	s_mul_hi_u32 s1, s9, s42
	s_add_i32 s1, s1, s0
	s_mul_i32 s0, s9, s42
	v_readlane_b32 s2, v249, 0
	s_add_u32 s88, s0, s2
	s_addc_u32 s89, s1, s93
	v_mov_b64_e32 v[2:3], 0x580
	v_cmp_lt_i64_e64 s[0:1], s[88:89], v[2:3]
	v_mov_b64_e32 v[2:3], 0x57f
	v_cmp_gt_i64_e64 s[2:3], s[88:89], v[2:3]
	v_mov_b64_e32 v[182:183], 0x100
	s_and_b64 vcc, exec, s[2:3]
	s_cbranch_vccnz .LBB0_61
	s_ashr_i32 s10, s88, 31
	s_lshr_b32 s10, s10, 29
	s_add_i32 s10, s88, s10
	s_ashr_i32 s11, s10, 3
	s_and_b32 s10, s10, -8
	s_sub_i32 s10, s88, s10
	s_cmp_lt_i32 s10, 0
	s_cselect_b32 s36, s51, 0xb0
	s_mul_i32 s10, s10, s36
	s_add_i32 s10, s10, s11
	s_mul_hi_i32 s11, s10, 0x2e8ba2e9
	s_lshr_b32 s36, s11, 31
	s_ashr_i32 s11, s11, 4
	s_add_i32 s11, s11, s36
	s_lshl_b32 s36, s11, 2
	s_mulk_i32 s11, 0x58
	s_sub_i32 s11, s10, s11
	s_lshr_b32 s10, s11, 2
	s_and_b32 s11, s11, 3
	s_add_i32 s38, s36, s11

; #define PG8_LAS __attribute__((address_space(3)))
;     __device__ __forceinline__ void issue(int k, bool wave0, int lane) const {
;         Unit u;
;         if (wave0 && S.next(k, u)) {
;             PG8_LAS unsigned char* slot = pf + (k & 1) * 5120;
; #pragma unroll
;             for (int q = 0; q < 4; ++q) __builtin_amdgcn_global_load_lds((const unsigned*)(rowss + (size_t)(u.pm * BM + 64 * q) * 4 + 4 * lane), (PG8_LAS unsigned*)(slot + 1024 * q), 16, 0, 0);
;             __builtin_amdgcn_global_load_lds((const unsigned*)(bias + (u.pm >> 3) * bstride + u.pn * BM + 4 * lane), (PG8_LAS unsigned*)(slot + 4096), 16, 0, 0);
;         }
;     __device__ __forceinline__ void operator()(const f32x4 (&acc)[2][2][4][2], const Unit& u, int wr, int wc, int fr, int fq) const {
;     ...
;         P.issue(k + 1, wr == 0 && wc == 0, fr + 16 * fq);
.LBB0_65:
	s_or_b64 s[2:3], s[74:75], s[2:3]
	s_and_b64 vcc, exec, s[2:3]
	v_mov_b64_e32 v[246:247], v[182:183]
	s_cbranch_vccnz .LBB0_67
	s_mov_b32 s30, s38
	s_mov_b32 s11, s10
	s_bitcmp1_b32 s9, 0
	s_cselect_b32 s2, 0x1400, 0
	s_add_i32 s31, s2, 0
	s_lshl_b32 s2, s30, 8
	s_ashr_i32 s3, s2, 31
	s_or_b32 s4, s2, 64
	s_add_i32 m0, s31, 0x20000
	v_lshl_add_u64 v[62:63], s[2:3], 4, v[152:153]
	s_ashr_i32 s5, s4, 31
	global_load_lds_dwordx4 v[62:63], off
	v_lshl_add_u64 v[62:63], s[4:5], 4, v[152:153]
	s_or_b32 s4, s2, 0x80
	s_add_i32 m0, s31, 0x20400
	s_ashr_i32 s5, s4, 31
	s_or_b32 s2, s2, 0xc0
	global_load_lds_dwordx4 v[62:63], off
	v_lshl_add_u64 v[62:63], s[4:5], 4, v[152:153]
	s_add_i32 m0, s31, 0x20800
	s_ashr_i32 s3, s2, 31
	global_load_lds_dwordx4 v[62:63], off
	v_lshl_add_u64 v[62:63], s[2:3], 4, v[152:153]
	s_lshr_b32 s2, s30, 3
	s_mulk_i32 s2, 0x1600
	s_ashr_i32 s3, s2, 31
	s_add_i32 m0, s31, 0x20c00
	s_lshl_b64 s[2:3], s[2:3], 2
	s_add_u32 s4, s58, s2
	s_addc_u32 s5, s59, s3
	s_lshl_b32 s2, s11, 8
	s_ashr_i32 s3, s2, 31
	s_lshl_b64 s[2:3], s[2:3], 2
	s_add_u32 s2, s4, s2
	global_load_lds_dwordx4 v[62:63], off
	s_addc_u32 s3, s5, s3
	s_add_i32 m0, s31, 0x21000
	s_nop 0
	global_load_lds_dwordx4 v166, s[2:3]

;     __host__ __device__ bool next(int i, Unit& u) const {
;         const long L = (long)i * G + c; if (L >= nwg) return false;
;         int wgid = (int)L; { const int q = nwg / NXCD, r = nwg % NXCD, xcd = wgid % NXCD, off = wgid / NXCD; wgid = (xcd < r ? xcd * (q + 1) : r * (q + 1) + (xcd - r) * q) + off; }
;         const int nig = WGM * nN, gid = wgid / nig, fm = gid * WGM, gsz = (nM - fm) < WGM ? (nM - fm) : WGM;
;         u.pm = fm + ((wgid % nig) % gsz); u.pn = (wgid % nig) / gsz; return true;
; template <class Epi, class Sched, bool ALIGN_EPI = false, bool SP2 = false>
; __device__ __forceinline__ void gemm_phase(PG8_LAS unsigned char* lds, const Gemm g, const Sched& S, const Epi& E, const int tid) {
;     ...
;         const bool has_next = S.next(ui + 1, nxt);
.LBB0_395:
	v_readlane_b32 s0, v249, 4
	v_readlane_b32 s1, v249, 5
	s_add_i32 s65, s68, 1
	s_mul_i32 s0, s65, s86
	s_mul_hi_u32 s1, s65, s42
	s_add_i32 s1, s1, s0
	s_mul_i32 s0, s65, s42
	v_readlane_b32 s2, v249, 0
	s_add_u32 s88, s0, s2
	s_addc_u32 s89, s1, s93
	v_mov_b64_e32 v[2:3], 0x300
	v_cmp_lt_i64_e64 s[0:1], s[88:89], v[2:3]
	v_mov_b64_e32 v[2:3], 0x2ff
	v_cmp_gt_i64_e64 s[2:3], s[88:89], v[2:3]
	s_mov_b64 s[4:5], s[70:71]
	s_and_b64 vcc, exec, s[2:3]
	s_cbranch_vccnz .LBB0_397
	s_ashr_i32 s10, s88, 31
	s_lshr_b32 s10, s10, 29
	s_add_i32 s10, s88, s10
	s_ashr_i32 s11, s10, 3
	s_and_b32 s10, s10, -8
	s_sub_i32 s10, s88, s10
	s_cmp_lt_i32 s10, 0
	s_movk_i32 s38, 0x61
	s_cselect_b32 s38, s38, 0x60
	s_mul_i32 s10, s10, s38
	s_add_i32 s10, s10, s11
	s_mul_hi_i32 s11, s10, 0x2aaaaaab
	s_lshr_b32 s38, s11, 31
	s_ashr_i32 s11, s11, 3
	s_add_i32 s11, s11, s38
	s_lshl_b32 s38, s11, 2
	s_mul_i32 s11, s11, 48
	s_sub_i32 s11, s10, s11
	s_lshr_b32 s10, s11, 2
	s_and_b32 s11, s11, 3
	s_add_i32 s38, s38, s11

; #define PG8_LAS __attribute__((address_space(3)))
;     __device__ __forceinline__ void issue(int k, bool wave0, int lane) const {
;         Unit u;
;         if (wave0 && S.next(k, u)) {
;             PG8_LAS unsigned char* slot = pf + (k & 1) * 5120;
; #pragma unroll
;             for (int q = 0; q < 4; ++q) __builtin_amdgcn_global_load_lds((const unsigned*)(rowss + (size_t)(u.pm * BM + 64 * q) * 4 + 4 * lane), (PG8_LAS unsigned*)(slot + 1024 * q), 16, 0, 0);
;             __builtin_amdgcn_global_load_lds((const unsigned*)(bias + (u.pm >> 3) * bstride + u.pn * BM + 4 * lane), (PG8_LAS unsigned*)(slot + 4096), 16, 0, 0);
;         }
;     __device__ __forceinline__ void operator()(const f32x4 (&acc)[2][2][4][2], const Unit& u, int wr, int wc, int fr, int fq) const {
;     ...
;         P.issue(k + 1, wr == 0 && wc == 0, fr + 16 * fq);
.LBB0_401:
	s_or_b64 s[2:3], s[8:9], s[2:3]
	s_and_b64 vcc, exec, s[2:3]
	s_mov_b64 s[70:71], s[4:5]
	s_cbranch_vccnz .LBB0_403
	v_readlane_b32 s4, v253, 29
	s_mov_b32 s11, s38
	s_mov_b32 s36, s10
	s_bitcmp1_b32 s65, 0
	s_cselect_b32 s2, 0x1400, 0
	s_add_i32 s37, s2, 0
	s_lshl_b32 s2, s11, 8
	s_ashr_i32 s3, s2, 31
	s_or_b32 s30, s2, 64
	s_add_i32 m0, s37, 0x20000
	v_lshl_add_u64 v[82:83], s[2:3], 4, v[196:197]
	s_ashr_i32 s31, s30, 31
	global_load_lds_dwordx4 v[82:83], off
	v_lshl_add_u64 v[82:83], s[30:31], 4, v[196:197]
	s_or_b32 s30, s2, 0x80
	s_add_i32 m0, s37, 0x20400
	s_ashr_i32 s31, s30, 31
	s_or_b32 s2, s2, 0xc0
	global_load_lds_dwordx4 v[82:83], off
	v_lshl_add_u64 v[82:83], s[30:31], 4, v[196:197]
	s_add_i32 m0, s37, 0x20800
	s_ashr_i32 s3, s2, 31
	global_load_lds_dwordx4 v[82:83], off
	v_lshl_add_u64 v[82:83], s[2:3], 4, v[196:197]
	s_lshr_b32 s2, s11, 3
	s_mulk_i32 s2, 0xc00
	s_ashr_i32 s3, s2, 31
	s_add_i32 m0, s37, 0x20c00
	s_lshl_b64 s[2:3], s[2:3], 2
	s_add_u32 s11, s4, s2
	v_readlane_b32 s2, v253, 30
	s_addc_u32 s30, s2, s3
	s_lshl_b32 s2, s36, 8
	s_ashr_i32 s3, s2, 31
	s_lshl_b64 s[2:3], s[2:3], 2
	s_add_u32 s2, s11, s2
	global_load_lds_dwordx4 v[82:83], off
	s_addc_u32 s3, s30, s3
	s_add_i32 m0, s37, 0x21000
	s_nop 0
	global_load_lds_dwordx4 v235, s[2:3]
